# phase 0 work redistribution: the 32 workgroups carrying a 4th filter item take the 3-round share of the w_in transposes (start tile (blk+128) mod 160)
# speedup vs baseline: 1.0017x; 1.0017x over previous
.LBB0_144:
	s_cmp_eq_u32 s34, 0x100
	s_cselect_b32 s69, 0x100, s69
	s_cbranch_scc0 .Lt_noremap
	s_cmpk_gt_u32 s20, 0xff
	s_cbranch_scc1 .Lt_noremap
	s_mov_b32 s101, s20
	s_addk_i32 s68, 0x80
	s_cmpk_ge_i32 s68, 0xa0
	s_cbranch_scc0 .Lt_nowrap
	s_addk_i32 s68, 0xff60
.Lt_nowrap:
	s_add_i32 s20, s68, 0x60

.LBB0_150:
	s_cmp_eq_u32 s34, 0x100
	s_cselect_b32 s20, s101, s20
	s_mov_b64 s[0:1], 0
